# k22 plus: the nine GEMM K-loop heads aligned to 64 bytes (code placement)
# speedup vs baseline: 1.0114x; 1.0022x over previous
;     __device__ bool next(int i, Unit& u) const { const bool r = base.next(i >> 1, u); u.kh = i & 1; return r; }
; template <class Epi, class Sched, bool ALIGN_EPI = false, bool SP2 = false, bool ABLK = false, bool F8 = false>
; __device__ __forceinline__ void gemm_phase(PG8_LAS unsigned char* lds, const Gemm g, const Sched& S, const Epi& E, const int wave_s) {
;     ...
;         const bool has_next = S.next(ui + 1, nxt); nxt.par = (ui + 1) & 1;
;         const char* nA = has_next ? (const char*)g.A + (size_t)nxt.pm * tstep + nxt.kh * khbA : cA; const char* nB = has_next ? (const char*)g.Bt + (size_t)nxt.pn * tstep + nxt.kh * khb : cB;
;         for (int t = 0; t < nt; t += 2) {
;             const bool last = (t == nt - 2);
;             const char* a1 = cA + (size_t)(t + 1) * kstepA;
;             const char* a2 = last ? nA : cA + (size_t)(t + 2) * kstepA; const char* b2 = last ? nB : cB + (size_t)(t + 2) * kstep;
;             const char* a3 = a2 + kstepA; const char* b3 = b2 + kstep;
;             if (last && has_next) { S.a_ready(nxt); if constexpr (Epi::PREF) E.prefetch(nxt, wid, lane); }
;     ...
;         if (!(Epi::MID && cur.kh == 0))
; #pragma unroll
;         for (int a = 0; a < 2; ++a)
; #pragma unroll
;             for (int b = 0; b < 2; ++b)
; #pragma unroll
;                 for (int m = 0; m < 4; ++m)
; #pragma unroll
;                     for (int n = 0; n < 2; ++n) acc[a][b][m][n] = (f32x4){0.f, 0.f, 0.f, 0.f};
;         cur = nxt; cA = nA; cB = nB; ++ui;
.LBB0_222:
	s_ashr_i32 s49, s48, 31
	s_and_b32 s67, s66, 1
	s_lshl_b64 s[50:51], s[48:49], 20
	s_add_u32 s50, s28, s50
	s_addc_u32 s51, s29, s51
	s_and_b64 s[52:53], exec, s[8:9]
	s_cselect_b32 s49, s59, s51
	s_cselect_b32 s77, s58, s50
	s_ashr_i32 s17, s16, 31
	s_lshl_b64 s[52:53], s[16:17], 20
	s_add_u32 s52, s18, s52
	s_addc_u32 s53, s21, s53
	s_and_b64 s[62:63], exec, s[8:9]
	s_cselect_b32 s17, s61, s53
	s_cselect_b32 s78, s60, s52
	s_lshl_b32 s62, s48, 8
	s_ashr_i32 s63, s62, 31
	s_lshl_b32 s72, s67, 10
	s_or_b64 s[8:9], s[44:45], s[8:9]
	s_add_u32 s58, s58, 0x80080
	s_addc_u32 s59, s59, 0
	s_add_u32 s79, s60, 0x100
	v_mov_b64_e32 v[0:1], 0
	s_addc_u32 s80, s61, 0
	s_mov_b32 s81, -2
	s_add_i32 s82, s95, s72
	v_mov_b64_e32 v[2:3], 0
	v_mov_b64_e32 v[8:9], 0
	v_mov_b64_e32 v[10:11], 0
	v_mov_b64_e32 v[16:17], 0
	v_mov_b64_e32 v[18:19], 0
	v_mov_b64_e32 v[24:25], 0
	v_mov_b64_e32 v[26:27], 0
	v_mov_b64_e32 v[32:33], 0
	v_mov_b64_e32 v[34:35], 0
	v_mov_b64_e32 v[40:41], 0
	v_mov_b64_e32 v[42:43], 0
	v_mov_b64_e32 v[48:49], 0
	v_mov_b64_e32 v[50:51], 0
	v_mov_b64_e32 v[56:57], 0
	v_mov_b64_e32 v[58:59], 0
	v_mov_b64_e32 v[4:5], 0
	v_mov_b64_e32 v[6:7], 0
	v_mov_b64_e32 v[12:13], 0
	v_mov_b64_e32 v[14:15], 0
	v_mov_b64_e32 v[20:21], 0
	v_mov_b64_e32 v[22:23], 0
	v_mov_b64_e32 v[28:29], 0
	v_mov_b64_e32 v[30:31], 0
	v_mov_b64_e32 v[36:37], 0
	v_mov_b64_e32 v[38:39], 0
	v_mov_b64_e32 v[44:45], 0
	v_mov_b64_e32 v[46:47], 0
	v_mov_b64_e32 v[52:53], 0
	v_mov_b64_e32 v[54:55], 0
	v_mov_b64_e32 v[60:61], 0
	v_mov_b64_e32 v[62:63], 0
	v_mov_b64_e32 v[64:65], 0
	v_mov_b64_e32 v[66:67], 0
	v_mov_b64_e32 v[72:73], 0
	v_mov_b64_e32 v[74:75], 0
	v_mov_b64_e32 v[80:81], 0
	v_mov_b64_e32 v[82:83], 0
	v_mov_b64_e32 v[88:89], 0
	v_mov_b64_e32 v[90:91], 0
	v_mov_b64_e32 v[96:97], 0
	v_mov_b64_e32 v[98:99], 0
	v_mov_b64_e32 v[104:105], 0
	v_mov_b64_e32 v[106:107], 0
	v_mov_b64_e32 v[112:113], 0
	v_mov_b64_e32 v[114:115], 0
	v_mov_b64_e32 v[120:121], 0
	v_mov_b64_e32 v[122:123], 0
	v_mov_b64_e32 v[68:69], 0
	v_mov_b64_e32 v[70:71], 0
	v_mov_b64_e32 v[76:77], 0
	v_mov_b64_e32 v[78:79], 0
	v_mov_b64_e32 v[84:85], 0
	v_mov_b64_e32 v[86:87], 0
	v_mov_b64_e32 v[92:93], 0
	v_mov_b64_e32 v[94:95], 0
	v_mov_b64_e32 v[100:101], 0
	v_mov_b64_e32 v[102:103], 0
	v_mov_b64_e32 v[108:109], 0
	v_mov_b64_e32 v[110:111], 0
	v_mov_b64_e32 v[116:117], 0
	v_mov_b64_e32 v[118:119], 0
	v_mov_b64_e32 v[124:125], 0
	v_mov_b64_e32 v[126:127], 0
	v_lshl_add_u64 v[154:155], s[62:63], 2, v[146:147]
	s_branch .LBB0_224
	.p2align	6

; template <class Epi, class Sched, bool ALIGN_EPI = false, bool SP2 = false, bool ABLK = false, bool F8 = false>
; __device__ __forceinline__ void gemm_phase(PG8_LAS unsigned char* lds, const Gemm g, const Sched& S, const Epi& E, const int wave_s) {
;     ...
;         for (int a = 0; a < 2; ++a)
; #pragma unroll
;             for (int b = 0; b < 2; ++b)
; #pragma unroll
;                 for (int m = 0; m < 4; ++m)
; #pragma unroll
;                     for (int n = 0; n < 2; ++n) acc[a][b][m][n] = (f32x4){0.f, 0.f, 0.f, 0.f};
;         cur = nxt; cA = nA; cB = nB; ++ui;
.LBB0_303:
	s_add_u32 s67, s50, 0x100
	s_addc_u32 s76, s51, 0
	s_add_u32 s50, s52, 0xc000
	v_mov_b64_e32 v[0:1], 0
	s_addc_u32 s51, s53, 0
	s_mov_b32 s77, -2
	s_waitcnt lgkmcnt(0)
	v_mov_b64_e32 v[2:3], 0
	v_mov_b64_e32 v[4:5], 0
	v_mov_b64_e32 v[6:7], 0
	v_mov_b64_e32 v[16:17], 0
	v_mov_b64_e32 v[18:19], 0
	v_mov_b64_e32 v[20:21], 0
	v_mov_b64_e32 v[22:23], 0
	v_mov_b64_e32 v[32:33], 0
	v_mov_b64_e32 v[34:35], 0
	v_mov_b64_e32 v[36:37], 0
	v_mov_b64_e32 v[38:39], 0
	v_mov_b64_e32 v[48:49], 0
	v_mov_b64_e32 v[50:51], 0
	v_mov_b64_e32 v[52:53], 0
	v_mov_b64_e32 v[54:55], 0
	v_mov_b64_e32 v[8:9], 0
	v_mov_b64_e32 v[10:11], 0
	v_mov_b64_e32 v[12:13], 0
	v_mov_b64_e32 v[14:15], 0
	v_mov_b64_e32 v[24:25], 0
	v_mov_b64_e32 v[26:27], 0
	v_mov_b64_e32 v[28:29], 0
	v_mov_b64_e32 v[30:31], 0
	v_mov_b64_e32 v[40:41], 0
	v_mov_b64_e32 v[42:43], 0
	v_mov_b64_e32 v[44:45], 0
	v_mov_b64_e32 v[46:47], 0
	v_mov_b64_e32 v[56:57], 0
	v_mov_b64_e32 v[58:59], 0
	v_mov_b64_e32 v[60:61], 0
	v_mov_b64_e32 v[62:63], 0
	v_mov_b64_e32 v[64:65], 0
	v_mov_b64_e32 v[66:67], 0
	v_mov_b64_e32 v[68:69], 0
	v_mov_b64_e32 v[70:71], 0
	v_mov_b64_e32 v[80:81], 0
	v_mov_b64_e32 v[82:83], 0
	v_mov_b64_e32 v[84:85], 0
	v_mov_b64_e32 v[86:87], 0
	v_mov_b64_e32 v[96:97], 0
	v_mov_b64_e32 v[98:99], 0
	v_mov_b64_e32 v[100:101], 0
	v_mov_b64_e32 v[102:103], 0
	v_mov_b64_e32 v[120:121], 0
	v_mov_b64_e32 v[122:123], 0
	v_mov_b64_e32 v[124:125], 0
	v_mov_b64_e32 v[126:127], 0
	v_mov_b64_e32 v[72:73], 0
	v_mov_b64_e32 v[74:75], 0
	v_mov_b64_e32 v[76:77], 0
	v_mov_b64_e32 v[78:79], 0
	v_mov_b64_e32 v[88:89], 0
	v_mov_b64_e32 v[90:91], 0
	v_mov_b64_e32 v[92:93], 0
	v_mov_b64_e32 v[94:95], 0
	v_mov_b64_e32 v[108:109], 0
	v_mov_b64_e32 v[110:111], 0
	v_mov_b64_e32 v[112:113], 0
	v_mov_b64_e32 v[114:115], 0
	v_mov_b64_e32 v[132:133], 0
	v_mov_b64_e32 v[134:135], 0
	v_mov_b64_e32 v[136:137], 0
	v_mov_b64_e32 v[138:139], 0
	.p2align	6

;     __device__ bool next(int i, Unit& u) const { const bool r = base.next(i >> 1, u); u.kh = i & 1; return r; }
; template <class Epi, class Sched, bool ALIGN_EPI = false, bool SP2 = false, bool ABLK = false, bool F8 = false>
; __device__ __forceinline__ void gemm_phase(PG8_LAS unsigned char* lds, const Gemm g, const Sched& S, const Epi& E, const int wave_s) {
;     ...
;         const bool has_next = S.next(ui + 1, nxt); nxt.par = (ui + 1) & 1;
;         const char* nA = has_next ? (const char*)g.A + (size_t)nxt.pm * tstep + nxt.kh * khbA : cA; const char* nB = has_next ? (const char*)g.Bt + (size_t)nxt.pn * tstep + nxt.kh * khb : cB;
;     ...
;         for (int a = 0; a < 2; ++a)
; #pragma unroll
;             for (int b = 0; b < 2; ++b)
; #pragma unroll
;                 for (int m = 0; m < 4; ++m)
; #pragma unroll
;                     for (int n = 0; n < 2; ++n) acc[a][b][m][n] = (f32x4){0.f, 0.f, 0.f, 0.f};
;         cur = nxt; cA = nA; cB = nB; ++ui;
.LBB0_394:
	s_ashr_i32 s53, s52, 31
	s_lshl_b64 s[54:55], s[52:53], 20
	s_add_u32 s54, s28, s54
	s_addc_u32 s55, s29, s55
	s_and_b64 s[56:57], s[10:11], exec
	s_cselect_b32 s20, s55, s63
	s_cselect_b32 s23, s54, s62
	s_ashr_i32 s51, s50, 31
	s_lshl_b64 s[56:57], s[50:51], 20
	s_add_u32 s56, s76, s56
	s_addc_u32 s57, s77, s57
	s_and_b64 s[66:67], s[10:11], exec
	s_cselect_b32 s51, s57, s65
	s_cselect_b32 s53, s56, s64
	s_add_u32 s62, s62, 0x80080
	s_addc_u32 s63, s63, 0
	s_add_u32 s59, s64, 0x100
	v_mov_b64_e32 v[0:1], 0
	s_addc_u32 s61, s65, 0
	s_mov_b32 vcc_lo, -2
	v_mov_b64_e32 v[2:3], 0
	v_mov_b64_e32 v[4:5], 0
	v_mov_b64_e32 v[6:7], 0
	v_mov_b64_e32 v[16:17], 0
	v_mov_b64_e32 v[18:19], 0
	v_mov_b64_e32 v[20:21], 0
	v_mov_b64_e32 v[22:23], 0
	v_mov_b64_e32 v[32:33], 0
	v_mov_b64_e32 v[34:35], 0
	v_mov_b64_e32 v[36:37], 0
	v_mov_b64_e32 v[38:39], 0
	v_mov_b64_e32 v[48:49], 0
	v_mov_b64_e32 v[50:51], 0
	v_mov_b64_e32 v[52:53], 0
	v_mov_b64_e32 v[54:55], 0
	v_mov_b64_e32 v[8:9], 0
	v_mov_b64_e32 v[10:11], 0
	v_mov_b64_e32 v[12:13], 0
	v_mov_b64_e32 v[14:15], 0
	v_mov_b64_e32 v[24:25], 0
	v_mov_b64_e32 v[26:27], 0
	v_mov_b64_e32 v[28:29], 0
	v_mov_b64_e32 v[30:31], 0
	v_mov_b64_e32 v[40:41], 0
	v_mov_b64_e32 v[42:43], 0
	v_mov_b64_e32 v[44:45], 0
	v_mov_b64_e32 v[46:47], 0
	v_mov_b64_e32 v[56:57], 0
	v_mov_b64_e32 v[58:59], 0
	v_mov_b64_e32 v[60:61], 0
	v_mov_b64_e32 v[62:63], 0
	v_mov_b64_e32 v[64:65], 0
	v_mov_b64_e32 v[66:67], 0
	v_mov_b64_e32 v[68:69], 0
	v_mov_b64_e32 v[70:71], 0
	v_mov_b64_e32 v[80:81], 0
	v_mov_b64_e32 v[82:83], 0
	v_mov_b64_e32 v[84:85], 0
	v_mov_b64_e32 v[86:87], 0
	v_mov_b64_e32 v[96:97], 0
	v_mov_b64_e32 v[98:99], 0
	v_mov_b64_e32 v[100:101], 0
	v_mov_b64_e32 v[102:103], 0
	v_mov_b64_e32 v[112:113], 0
	v_mov_b64_e32 v[114:115], 0
	v_mov_b64_e32 v[116:117], 0
	v_mov_b64_e32 v[118:119], 0
	v_mov_b64_e32 v[72:73], 0
	v_mov_b64_e32 v[74:75], 0
	v_mov_b64_e32 v[76:77], 0
	v_mov_b64_e32 v[78:79], 0
	v_mov_b64_e32 v[88:89], 0
	v_mov_b64_e32 v[90:91], 0
	v_mov_b64_e32 v[92:93], 0
	v_mov_b64_e32 v[94:95], 0
	v_mov_b64_e32 v[104:105], 0
	v_mov_b64_e32 v[106:107], 0
	v_mov_b64_e32 v[108:109], 0
	v_mov_b64_e32 v[110:111], 0
	v_mov_b64_e32 v[120:121], 0
	v_mov_b64_e32 v[122:123], 0
	v_mov_b64_e32 v[124:125], 0
	v_mov_b64_e32 v[126:127], 0
	.p2align	6

;     __device__ bool next(int i, Unit& u) const { const bool r = base.next(i >> 1, u); u.kh = i & 1; return r; }
; template <class Epi, class Sched, bool ALIGN_EPI = false, bool SP2 = false, bool ABLK = false, bool F8 = false>
; __device__ __forceinline__ void gemm_phase(PG8_LAS unsigned char* lds, const Gemm g, const Sched& S, const Epi& E, const int wave_s) {
;     ...
;         const bool has_next = S.next(ui + 1, nxt); nxt.par = (ui + 1) & 1;
;         const char* nA = has_next ? (const char*)g.A + (size_t)nxt.pm * tstep + nxt.kh * khbA : cA; const char* nB = has_next ? (const char*)g.Bt + (size_t)nxt.pn * tstep + nxt.kh * khb : cB;
;     ...
;         for (int a = 0; a < 2; ++a)
; #pragma unroll
;             for (int b = 0; b < 2; ++b)
; #pragma unroll
;                 for (int m = 0; m < 4; ++m)
; #pragma unroll
;                     for (int n = 0; n < 2; ++n) acc[a][b][m][n] = (f32x4){0.f, 0.f, 0.f, 0.f};
;         cur = nxt; cA = nA; cB = nB; ++ui;
.LBB0_591:
	s_ashr_i32 s51, s50, 31
	s_lshl_b64 s[52:53], s[50:51], 19
	s_add_u32 s52, s12, s52
	s_addc_u32 s53, s13, s53
	s_and_b64 s[54:55], s[10:11], exec
	s_cselect_b32 s51, s53, s61
	s_cselect_b32 s57, s52, s60
	s_ashr_i32 s49, s48, 31
	s_lshl_b64 s[54:55], s[48:49], 19
	s_add_u32 s54, s18, s54
	s_addc_u32 s55, s19, s55
	s_and_b64 s[64:65], s[10:11], exec
	s_cselect_b32 s49, s55, s63
	s_cselect_b32 s67, s54, s62
	s_add_u32 s60, s60, 0x40080
	s_addc_u32 s61, s61, 0
	s_add_u32 s74, s62, 0x100
	v_mov_b64_e32 v[0:1], 0
	s_addc_u32 s75, s63, 0
	s_mov_b32 s76, -2
	s_waitcnt lgkmcnt(0)
	v_mov_b64_e32 v[2:3], 0
	v_mov_b64_e32 v[4:5], 0
	v_mov_b64_e32 v[6:7], 0
	s_waitcnt vmcnt(0)
	v_mov_b64_e32 v[16:17], 0
	v_mov_b64_e32 v[18:19], 0
	v_mov_b64_e32 v[20:21], 0
	v_mov_b64_e32 v[22:23], 0
	v_mov_b64_e32 v[32:33], 0
	v_mov_b64_e32 v[34:35], 0
	v_mov_b64_e32 v[36:37], 0
	v_mov_b64_e32 v[38:39], 0
	v_mov_b64_e32 v[48:49], 0
	v_mov_b64_e32 v[50:51], 0
	v_mov_b64_e32 v[52:53], 0
	v_mov_b64_e32 v[54:55], 0
	v_mov_b64_e32 v[8:9], 0
	v_mov_b64_e32 v[10:11], 0
	v_mov_b64_e32 v[12:13], 0
	v_mov_b64_e32 v[14:15], 0
	v_mov_b64_e32 v[24:25], 0
	v_mov_b64_e32 v[26:27], 0
	v_mov_b64_e32 v[28:29], 0
	v_mov_b64_e32 v[30:31], 0
	v_mov_b64_e32 v[40:41], 0
	v_mov_b64_e32 v[42:43], 0
	v_mov_b64_e32 v[44:45], 0
	v_mov_b64_e32 v[46:47], 0
	v_mov_b64_e32 v[56:57], 0
	v_mov_b64_e32 v[58:59], 0
	v_mov_b64_e32 v[60:61], 0
	v_mov_b64_e32 v[62:63], 0
	v_mov_b64_e32 v[72:73], 0
	v_mov_b64_e32 v[74:75], 0
	v_mov_b64_e32 v[84:85], 0
	v_mov_b64_e32 v[86:87], 0
	v_mov_b64_e32 v[104:105], 0
	v_mov_b64_e32 v[106:107], 0
	v_mov_b64_e32 v[108:109], 0
	v_mov_b64_e32 v[110:111], 0
	v_mov_b64_e32 v[128:129], 0
	v_mov_b64_e32 v[130:131], 0
	v_mov_b64_e32 v[132:133], 0
	v_mov_b64_e32 v[134:135], 0
	v_mov_b64_e32 v[152:153], 0
	v_mov_b64_e32 v[154:155], 0
	v_mov_b64_e32 v[156:157], 0
	v_mov_b64_e32 v[158:159], 0
	v_mov_b64_e32 v[92:93], 0
	v_mov_b64_e32 v[94:95], 0
	v_mov_b64_e32 v[96:97], 0
	v_mov_b64_e32 v[98:99], 0
	v_mov_b64_e32 v[116:117], 0
	v_mov_b64_e32 v[118:119], 0
	v_mov_b64_e32 v[120:121], 0
	v_mov_b64_e32 v[122:123], 0
	v_mov_b64_e32 v[140:141], 0
	v_mov_b64_e32 v[142:143], 0
	v_mov_b64_e32 v[148:149], 0
	v_mov_b64_e32 v[150:151], 0
	v_mov_b64_e32 v[168:169], 0
	v_mov_b64_e32 v[170:171], 0
	v_mov_b64_e32 v[172:173], 0
	v_mov_b64_e32 v[174:175], 0
	.p2align	6

;     __device__ bool next(int i, Unit& u) const { const bool r = base.next(i >> 1, u); u.kh = i & 1; return r; }
; template <class Epi, class Sched, bool ALIGN_EPI = false, bool SP2 = false, bool ABLK = false, bool F8 = false>
; __device__ __forceinline__ void gemm_phase(PG8_LAS unsigned char* lds, const Gemm g, const Sched& S, const Epi& E, const int wave_s) {
;     ...
;         const bool has_next = S.next(ui + 1, nxt); nxt.par = (ui + 1) & 1;
;         const char* nA = has_next ? (const char*)g.A + (size_t)nxt.pm * tstep + nxt.kh * khbA : cA; const char* nB = has_next ? (const char*)g.Bt + (size_t)nxt.pn * tstep + nxt.kh * khb : cB;
.LBB0_685:
	s_ashr_i32 s57, s56, 31
	s_and_b32 s77, s76, 1
	s_lshl_b64 s[58:59], s[56:57], 20
	s_add_u32 s13, s14, s58
	s_addc_u32 s55, s15, s59
	s_lshl_b32 s66, s77, 11
	s_add_u32 s58, s13, s66
	s_addc_u32 s59, s55, 0
	s_and_b64 s[60:61], s[8:9], exec
	s_cselect_b32 s13, s59, s63
	s_cselect_b32 s57, s58, s62
	s_ashr_i32 s55, s54, 31
	s_lshl_b64 s[60:61], s[54:55], 20
	s_add_u32 s55, s18, s60
	s_addc_u32 s61, s19, s61
	s_add_u32 s60, s55, s66
	s_addc_u32 s61, s61, 0
	s_and_b64 s[66:67], s[8:9], exec
	s_cselect_b32 s55, s61, s65
	s_cselect_b32 s78, s60, s64
	s_add_u32 s62, s62, 0x80080
	s_addc_u32 s63, s63, 0
	s_add_u32 s79, s64, 0x100
	s_addc_u32 s80, s65, 0
	s_mov_b32 s81, -2
	.p2align	6

;     __device__ bool next(int i, Unit& u) const { const bool r = base.next(i >> 1, u); u.kh = i & 1; return r; }
; template <class Epi, class Sched, bool ALIGN_EPI = false, bool SP2 = false, bool ABLK = false, bool F8 = false>
; __device__ __forceinline__ void gemm_phase(PG8_LAS unsigned char* lds, const Gemm g, const Sched& S, const Epi& E, const int wave_s) {
;     ...
;         const bool has_next = S.next(ui + 1, nxt); nxt.par = (ui + 1) & 1;
;         const char* nA = has_next ? (const char*)g.A + (size_t)nxt.pm * tstep + nxt.kh * khbA : cA; const char* nB = has_next ? (const char*)g.Bt + (size_t)nxt.pn * tstep + nxt.kh * khb : cB;
;         for (int t = 0; t < nt; t += 2) {
;             const bool last = (t == nt - 2);
;             const char* a1 = cA + (size_t)(t + 1) * kstepA;
;             const char* a2 = last ? nA : cA + (size_t)(t + 2) * kstepA; const char* b2 = last ? nB : cB + (size_t)(t + 2) * kstep;
;             const char* a3 = a2 + kstepA; const char* b3 = b2 + kstep;
;             if (last && has_next) { S.a_ready(nxt); if constexpr (Epi::PREF) E.prefetch(nxt, wid, lane); }
;     ...
;         if (!(Epi::MID && cur.kh == 0))
; #pragma unroll
;         for (int a = 0; a < 2; ++a)
; #pragma unroll
;             for (int b = 0; b < 2; ++b)
; #pragma unroll
;                 for (int m = 0; m < 4; ++m)
; #pragma unroll
;                     for (int n = 0; n < 2; ++n) acc[a][b][m][n] = (f32x4){0.f, 0.f, 0.f, 0.f};
;         cur = nxt; cA = nA; cB = nB; ++ui;
.LBB0_809:
	s_ashr_i32 s43, s42, 31
	s_and_b32 s64, s63, 1
	s_lshl_b64 s[46:47], s[42:43], 19
	s_add_u32 s46, s38, s46
	s_addc_u32 s47, s39, s47
	s_and_b64 s[48:49], exec, s[10:11]
	s_cselect_b32 s43, s55, s47
	s_cselect_b32 s66, s54, s46
	s_ashr_i32 s41, s40, 31
	s_lshl_b64 s[48:49], s[40:41], 19
	s_add_u32 s48, s18, s48
	s_addc_u32 s49, s19, s49
	s_and_b64 s[58:59], exec, s[10:11]
	s_cselect_b32 s41, s57, s49
	s_cselect_b32 s67, s56, s48
	s_lshl_b32 s58, s42, 8
	s_ashr_i32 s59, s58, 31
	s_lshl_b32 s75, s64, 10
	s_or_b64 s[10:11], s[44:45], s[10:11]
	s_add_u32 s54, s54, 0x40080
	s_addc_u32 s55, s55, 0
	s_add_u32 s72, s56, 0x100
	v_mov_b64_e32 v[0:1], 0
	v_lshl_add_u64 v[228:229], s[58:59], 2, v[130:131]
	s_addc_u32 s73, s57, 0
	s_mov_b32 s74, -2
	s_add_i32 s75, s95, s75
	v_mov_b64_e32 v[2:3], 0
	v_mov_b64_e32 v[8:9], 0
	v_mov_b64_e32 v[10:11], 0
	v_mov_b64_e32 v[16:17], 0
	v_mov_b64_e32 v[18:19], 0
	v_mov_b64_e32 v[24:25], 0
	v_mov_b64_e32 v[26:27], 0
	v_mov_b64_e32 v[32:33], 0
	v_mov_b64_e32 v[34:35], 0
	v_mov_b64_e32 v[40:41], 0
	v_mov_b64_e32 v[42:43], 0
	v_mov_b64_e32 v[48:49], 0
	v_mov_b64_e32 v[50:51], 0
	v_mov_b64_e32 v[56:57], 0
	v_mov_b64_e32 v[58:59], 0
	v_mov_b64_e32 v[4:5], 0
	v_mov_b64_e32 v[6:7], 0
	v_mov_b64_e32 v[12:13], 0
	v_mov_b64_e32 v[14:15], 0
	v_mov_b64_e32 v[20:21], 0
	v_mov_b64_e32 v[22:23], 0
	v_mov_b64_e32 v[28:29], 0
	v_mov_b64_e32 v[30:31], 0
	v_mov_b64_e32 v[36:37], 0
	v_mov_b64_e32 v[38:39], 0
	v_mov_b64_e32 v[44:45], 0
	v_mov_b64_e32 v[46:47], 0
	v_mov_b64_e32 v[52:53], 0
	v_mov_b64_e32 v[54:55], 0
	v_mov_b64_e32 v[60:61], 0
	v_mov_b64_e32 v[62:63], 0
	v_mov_b64_e32 v[64:65], 0
	v_mov_b64_e32 v[66:67], 0
	v_mov_b64_e32 v[72:73], 0
	v_mov_b64_e32 v[74:75], 0
	v_mov_b64_e32 v[80:81], 0
	v_mov_b64_e32 v[82:83], 0
	v_mov_b64_e32 v[88:89], 0
	v_mov_b64_e32 v[90:91], 0
	v_mov_b64_e32 v[96:97], 0
	v_mov_b64_e32 v[98:99], 0
	v_mov_b64_e32 v[104:105], 0
	v_mov_b64_e32 v[106:107], 0
	v_mov_b64_e32 v[112:113], 0
	v_mov_b64_e32 v[114:115], 0
	v_mov_b64_e32 v[120:121], 0
	v_mov_b64_e32 v[122:123], 0
	v_mov_b64_e32 v[68:69], 0
	v_mov_b64_e32 v[70:71], 0
	v_mov_b64_e32 v[76:77], 0
	v_mov_b64_e32 v[78:79], 0
	v_mov_b64_e32 v[84:85], 0
	v_mov_b64_e32 v[86:87], 0
	v_mov_b64_e32 v[92:93], 0
	v_mov_b64_e32 v[94:95], 0
	v_mov_b64_e32 v[100:101], 0
	v_mov_b64_e32 v[102:103], 0
	v_mov_b64_e32 v[108:109], 0
	v_mov_b64_e32 v[110:111], 0
	v_mov_b64_e32 v[116:117], 0
	v_mov_b64_e32 v[118:119], 0
	v_mov_b64_e32 v[124:125], 0
	v_mov_b64_e32 v[126:127], 0
	s_branch .LBB0_811
	.p2align	6

; template <class Epi, class Sched, bool ALIGN_EPI = false, bool SP2 = false, bool ABLK = false, bool F8 = false>
; __device__ __forceinline__ void gemm_phase(PG8_LAS unsigned char* lds, const Gemm g, const Sched& S, const Epi& E, const int wave_s) {
;     ...
;         for (int a = 0; a < 2; ++a)
; #pragma unroll
;             for (int b = 0; b < 2; ++b)
; #pragma unroll
;                 for (int m = 0; m < 4; ++m)
; #pragma unroll
;                     for (int n = 0; n < 2; ++n) acc[a][b][m][n] = (f32x4){0.f, 0.f, 0.f, 0.f};
;         cur = nxt; cA = nA; cB = nB; ++ui;
.LBB0_893:
	s_add_u32 s60, s44, 0x100
	s_addc_u32 s61, s45, 0
	s_add_u32 s44, s46, 0xc000
	v_mov_b64_e32 v[0:1], 0
	s_addc_u32 s45, s47, 0
	s_mov_b32 s62, -2
	s_waitcnt lgkmcnt(0)
	v_mov_b64_e32 v[2:3], 0
	v_mov_b64_e32 v[4:5], 0
	v_mov_b64_e32 v[6:7], 0
	v_mov_b64_e32 v[16:17], 0
	v_mov_b64_e32 v[18:19], 0
	v_mov_b64_e32 v[20:21], 0
	v_mov_b64_e32 v[22:23], 0
	v_mov_b64_e32 v[32:33], 0
	v_mov_b64_e32 v[34:35], 0
	v_mov_b64_e32 v[36:37], 0
	v_mov_b64_e32 v[38:39], 0
	v_mov_b64_e32 v[48:49], 0
	v_mov_b64_e32 v[50:51], 0
	v_mov_b64_e32 v[52:53], 0
	v_mov_b64_e32 v[54:55], 0
	v_mov_b64_e32 v[8:9], 0
	v_mov_b64_e32 v[10:11], 0
	v_mov_b64_e32 v[12:13], 0
	v_mov_b64_e32 v[14:15], 0
	v_mov_b64_e32 v[24:25], 0
	v_mov_b64_e32 v[26:27], 0
	v_mov_b64_e32 v[28:29], 0
	v_mov_b64_e32 v[30:31], 0
	v_mov_b64_e32 v[40:41], 0
	v_mov_b64_e32 v[42:43], 0
	v_mov_b64_e32 v[44:45], 0
	v_mov_b64_e32 v[46:47], 0
	v_mov_b64_e32 v[56:57], 0
	v_mov_b64_e32 v[58:59], 0
	v_mov_b64_e32 v[60:61], 0
	v_mov_b64_e32 v[62:63], 0
	v_mov_b64_e32 v[64:65], 0
	v_mov_b64_e32 v[66:67], 0
	v_mov_b64_e32 v[68:69], 0
	v_mov_b64_e32 v[70:71], 0
	v_mov_b64_e32 v[80:81], 0
	v_mov_b64_e32 v[82:83], 0
	v_mov_b64_e32 v[84:85], 0
	v_mov_b64_e32 v[86:87], 0
	v_mov_b64_e32 v[96:97], 0
	v_mov_b64_e32 v[98:99], 0
	v_mov_b64_e32 v[100:101], 0
	v_mov_b64_e32 v[102:103], 0
	v_mov_b64_e32 v[120:121], 0
	v_mov_b64_e32 v[122:123], 0
	v_mov_b64_e32 v[124:125], 0
	v_mov_b64_e32 v[126:127], 0
	v_mov_b64_e32 v[72:73], 0
	v_mov_b64_e32 v[74:75], 0
	v_mov_b64_e32 v[76:77], 0
	v_mov_b64_e32 v[78:79], 0
	v_mov_b64_e32 v[88:89], 0
	v_mov_b64_e32 v[90:91], 0
	v_mov_b64_e32 v[92:93], 0
	v_mov_b64_e32 v[94:95], 0
	v_mov_b64_e32 v[108:109], 0
	v_mov_b64_e32 v[110:111], 0
	v_mov_b64_e32 v[112:113], 0
	v_mov_b64_e32 v[114:115], 0
	v_mov_b64_e32 v[132:133], 0
	v_mov_b64_e32 v[134:135], 0
	v_mov_b64_e32 v[136:137], 0
	v_mov_b64_e32 v[138:139], 0
	.p2align	6

;     __host__ __device__ bool next(int i, Unit& u) const {
;     ...
;         int wgid = (int)L; { const int q = nwg / NXCD, r = nwg % NXCD, xcd = wgid % NXCD, off = wgid / NXCD; wgid = (xcd < r ? xcd * (q + 1) : r * (q + 1) + (xcd - r) * q) + off; }
;         const int nig = WGM * nN, gid = wgid / nig, fm = gid * WGM, gsz = (nM - fm) < WGM ? (nM - fm) : WGM;
;         u.pm = fm + ((wgid % nig) % gsz); u.pn = (wgid % nig) / gsz; u.kh = 0; return true;
.LBB0_984:
	s_ashr_i32 s50, s52, 3
	s_add_i32 s50, s54, s50
	s_ashr_i32 s51, s50, 31
	s_lshr_b32 s51, s51, 26
	s_add_i32 s51, s50, s51
	s_ashr_i32 s52, s51, 6
	s_lshl_b32 s52, s52, 3
	s_sub_i32 s53, 0x80, s52
	s_min_i32 s53, s53, 8
	s_abs_i32 s54, s53
	v_cvt_f32_u32_e32 v0, s54
	s_sub_i32 s56, 0, s54
	s_andn2_b32 s51, s51, 63
	s_sub_i32 s51, s50, s51
	v_rcp_iflag_f32_e32 v0, v0
	s_abs_i32 s50, s51
	s_xor_b32 s55, s51, s53
	s_ashr_i32 s55, s55, 31
	v_mul_f32_e32 v0, 0x4f7ffffe, v0
	v_cvt_u32_f32_e32 v0, v0
	s_nop 0
	v_readfirstlane_b32 s57, v0
	s_mul_i32 s56, s56, s57
	s_mul_hi_u32 s56, s57, s56
	s_add_i32 s57, s57, s56
	s_mul_hi_u32 s56, s50, s57
	s_mul_i32 s57, s56, s54
	s_sub_i32 s50, s50, s57
	s_add_i32 s62, s56, 1
	s_sub_i32 s57, s50, s54
	s_cmp_ge_u32 s50, s54
	s_cselect_b32 s56, s62, s56
	s_cselect_b32 s50, s57, s50
	s_add_i32 s57, s56, 1
	s_cmp_ge_u32 s50, s54
	s_cselect_b32 s50, s57, s56
	s_xor_b32 s50, s50, s55
	s_sub_i32 s50, s50, s55
	s_mul_i32 s53, s50, s53
	s_sub_i32 s51, s51, s53
	s_add_i32 s52, s52, s51
	.p2align	6

;     __device__ bool next(int i, Unit& u) const { const bool r = base.next(i >> 1, u); u.kh = i & 1; return r; }
; template <class Epi, class Sched, bool ALIGN_EPI = false, bool SP2 = false, bool ABLK = false, bool F8 = false>
; __device__ __forceinline__ void gemm_phase(PG8_LAS unsigned char* lds, const Gemm g, const Sched& S, const Epi& E, const int wave_s) {
;     ...
;         const bool has_next = S.next(ui + 1, nxt); nxt.par = (ui + 1) & 1;
;         const char* nA = has_next ? (const char*)g.A + (size_t)nxt.pm * tstep + nxt.kh * khbA : cA; const char* nB = has_next ? (const char*)g.Bt + (size_t)nxt.pn * tstep + nxt.kh * khb : cB;
;     ...
;         for (int a = 0; a < 2; ++a)
; #pragma unroll
;             for (int b = 0; b < 2; ++b)
; #pragma unroll
;                 for (int m = 0; m < 4; ++m)
; #pragma unroll
;                     for (int n = 0; n < 2; ++n) acc[a][b][m][n] = (f32x4){0.f, 0.f, 0.f, 0.f};
;         cur = nxt; cA = nA; cB = nB; ++ui;
.LBB0_1009:
	s_ashr_i32 s41, s40, 31
	s_lshl_b64 s[42:43], s[40:41], 20
	s_add_u32 s42, s28, s42
	s_addc_u32 s43, s29, s43
	s_and_b64 s[44:45], s[6:7], exec
	s_cselect_b32 s41, s43, s51
	s_cselect_b32 s47, s42, s50
	s_ashr_i32 s13, s12, 31
	s_lshl_b64 s[44:45], s[12:13], 20
	s_add_u32 s44, s18, s44
	s_addc_u32 s45, s19, s45
	s_and_b64 s[54:55], s[6:7], exec
	s_cselect_b32 s13, s45, s53
	s_cselect_b32 s59, s44, s52
	s_add_u32 s50, s50, 0x80080
	s_addc_u32 s51, s51, 0
	s_add_u32 s60, s52, 0x100
	v_mov_b64_e32 v[0:1], 0
	s_addc_u32 s61, s53, 0
	s_mov_b32 s62, -2
	s_waitcnt lgkmcnt(0)
	v_mov_b64_e32 v[2:3], 0
	v_mov_b64_e32 v[4:5], 0
	v_mov_b64_e32 v[6:7], 0
	v_mov_b64_e32 v[16:17], 0
	v_mov_b64_e32 v[18:19], 0
	v_mov_b64_e32 v[20:21], 0
	v_mov_b64_e32 v[22:23], 0
	v_mov_b64_e32 v[32:33], 0
	v_mov_b64_e32 v[34:35], 0
	v_mov_b64_e32 v[36:37], 0
	v_mov_b64_e32 v[38:39], 0
	v_mov_b64_e32 v[48:49], 0
	v_mov_b64_e32 v[50:51], 0
	v_mov_b64_e32 v[52:53], 0
	v_mov_b64_e32 v[54:55], 0
	v_mov_b64_e32 v[8:9], 0
	v_mov_b64_e32 v[10:11], 0
	v_mov_b64_e32 v[12:13], 0
	v_mov_b64_e32 v[14:15], 0
	v_mov_b64_e32 v[24:25], 0
	v_mov_b64_e32 v[26:27], 0
	v_mov_b64_e32 v[28:29], 0
	v_mov_b64_e32 v[30:31], 0
	v_mov_b64_e32 v[40:41], 0
	v_mov_b64_e32 v[42:43], 0
	v_mov_b64_e32 v[44:45], 0
	v_mov_b64_e32 v[46:47], 0
	v_mov_b64_e32 v[56:57], 0
	v_mov_b64_e32 v[58:59], 0
	v_mov_b64_e32 v[60:61], 0
	v_mov_b64_e32 v[62:63], 0
	v_mov_b64_e32 v[72:73], 0
	v_mov_b64_e32 v[74:75], 0
	v_mov_b64_e32 v[76:77], 0
	v_mov_b64_e32 v[78:79], 0
	v_mov_b64_e32 v[96:97], 0
	v_mov_b64_e32 v[98:99], 0
	v_mov_b64_e32 v[100:101], 0
	v_mov_b64_e32 v[102:103], 0
	v_mov_b64_e32 v[120:121], 0
	v_mov_b64_e32 v[122:123], 0
	v_mov_b64_e32 v[124:125], 0
	v_mov_b64_e32 v[126:127], 0
	v_mov_b64_e32 v[144:145], 0
	v_mov_b64_e32 v[146:147], 0
	v_mov_b64_e32 v[148:149], 0
	v_mov_b64_e32 v[150:151], 0
	v_mov_b64_e32 v[80:81], 0
	v_mov_b64_e32 v[82:83], 0
	v_mov_b64_e32 v[84:85], 0
	v_mov_b64_e32 v[86:87], 0
	v_mov_b64_e32 v[104:105], 0
	v_mov_b64_e32 v[106:107], 0
	v_mov_b64_e32 v[108:109], 0
	v_mov_b64_e32 v[110:111], 0
	v_mov_b64_e32 v[128:129], 0
	v_mov_b64_e32 v[130:131], 0
	v_mov_b64_e32 v[132:133], 0
	v_mov_b64_e32 v[134:135], 0
	v_mov_b64_e32 v[156:157], 0
	v_mov_b64_e32 v[158:159], 0
	v_mov_b64_e32 v[160:161], 0
	v_mov_b64_e32 v[162:163], 0
	.p2align	6
